# M1 retkv item head: 4th operand load hoisted to where its address is ready (all 4 loads in flight, counted waits vmcnt 3/2), both layers
# speedup vs baseline: 1.0052x; 1.0052x over previous
; __device__ __forceinline__ float bflo(unsigned w) { return __uint_as_float(w << 16); }
; __device__ __forceinline__ float bfhi(unsigned w) { return __uint_as_float(w & 0xffff0000u); }
; __device__ __forceinline__ unsigned short f2bf(float f) { return (unsigned short)(cvt_pk_bf16(f, 0.f) & 0xffffu); }
; __device__ __forceinline__ void retkv_item(PRef p, int layer, int item, unsigned char* shm) {
;     ...
;     const float lgf = -expf(p.in[17][(layer * 2 + 0) * 8 + h]), lgb = -expf(p.in[17][(layer * 2 + 1) * 8 + h]);
;     const bf16_t* A = (const bf16_t*)(p.ws + O_A);
;     bf16_t* kTf = (bf16_t*)shm; bf16_t* kTb = kTf + 64 * LDK; bf16_t* vT = kTb + 64 * LDK;
; #pragma unroll
;     for (int i = 0; i < 2; ++i) { const int idx = tid + 512 * i, m = idx >> 3, d8 = (idx & 7) * 8;
;         const u32x4 v = *(const u32x4*)(A + (size_t)(row0 + m) * NIN + C_K + h * 64 + d8);
;         const float pf = 0.125f * expf((float)(127 - m) * lgf), pb = 0.125f * expf((float)m * lgb);
;         const unsigned ww[4] = {v.x, v.y, v.z, v.w};
; #pragma unroll
;         for (int j = 0; j < 4; ++j) { const float lo = bflo(ww[j]), hi = bfhi(ww[j]);
;             kTf[tsw(d8 + 2 * j, m)] = f2bf(lo * pf); kTf[tsw(d8 + 2 * j + 1, m)] = f2bf(hi * pf);
;             kTb[tsw(d8 + 2 * j, m)] = f2bf(lo * pb); kTb[tsw(d8 + 2 * j + 1, m)] = f2bf(hi * pb); } }
.LBB0_261:
	s_and_b32 s4, s4, 7
	s_lshl_b32 s10, s4, 2
	v_mov_b32_e32 v0, s10
	global_load_dword v14, v0, s[8:9]
	global_load_dword v15, v0, s[8:9] offset:32
	v_ashrrev_i32_e32 v2, 3, v6
	v_lshlrev_b32_e32 v9, 3, v6
	v_mov_b64_e32 v[4:5], s[16:17]
	v_add_u32_e32 v0, s5, v2
	v_and_b32_e32 v16, 56, v9
	s_lshl_b32 s10, s4, 7
	v_mad_i64_i32 v[0:1], s[22:23], v0, s29, v[4:5]
	v_lshlrev_b32_e32 v132, 1, v16
	v_lshl_add_u64 v[0:1], v[0:1], 0, s[10:11]
	v_lshl_add_u64 v[0:1], v[0:1], 0, v[132:133]
	v_add_co_u32_e32 v0, vcc, s30, v0
	v_add_u32_e32 v17, 0x200, v6
	s_nop 0
	v_addc_co_u32_e32 v1, vcc, 0, v1, vcc
	global_load_dwordx4 v[10:13], v[0:1], off
	v_sub_u32_e32 v0, 0x7f, v2
	v_ashrrev_i32_e32 v19, 3, v17
	v_cvt_f32_i32_e32 v20, v0
	v_add_u32_e32 v0, v16, v2
	v_add_u32_e32 v1, s5, v19
	v_and_b32_e32 v21, 0x7f, v0
	v_cvt_f32_i32_e32 v18, v2
	v_mad_i64_i32 v[0:1], s[22:23], v1, s29, v[4:5]
	v_mad_u32_u24 v2, v16, s31, v21
	v_lshl_add_u64 v[0:1], v[0:1], 0, s[10:11]
	v_lshl_add_u32 v22, v2, 1, 0
	v_lshl_add_u64 v[0:1], v[0:1], 0, v[132:133]
	v_add_co_u32_e32 v0, vcc, s30, v0
	v_ashrrev_i32_e32 v36, 4, v6
	s_nop 0
	v_addc_co_u32_e32 v1, vcc, 0, v1, vcc
	global_load_dwordx4 v[200:203], v[0:1], off
	v_and_b32_e32 v35, 0x78, v9
	s_lshl_b32 s10, s4, 8
	v_lshlrev_b32_e32 v132, 1, v35
	v_ashrrev_i32_e32 v37, 4, v17
	v_and_b32_e32 v8, 15, v6
	v_bfe_u32 v7, v6, 4, 2
	v_or_b32_e32 v52, 16, v8
	v_or_b32_e32 v54, 32, v8
	v_or_b32_e32 v56, 48, v8
	v_or_b32_e32 v58, 64, v8
	v_or_b32_e32 v60, 0x50, v8
	v_or_b32_e32 v63, 0x60, v8
	v_or_b32_e32 v65, 0x70, v8
	v_mad_u32_u24 v53, v8, s33, v140
	v_mad_u32_u24 v55, v8, s33, v141
	v_mad_u32_u24 v57, v8, s33, v142
	v_mad_u32_u24 v59, v8, s33, v143
	v_mad_u32_u24 v62, v8, s33, v144
	v_mad_u32_u24 v64, v8, s33, v145
	v_mad_u32_u24 v66, v8, s33, v146
	v_mul_u32_u24_e32 v67, 0x110, v8
	s_lshl_b32 s2, s2, 4
	s_lshl_b32 s4, s4, 1
	s_or_b32 s2, s2, s4
	s_waitcnt vmcnt(3)
	v_mul_f32_e32 v2, 0x3fb8aa3b, v14
	s_waitcnt vmcnt(2)
	v_mul_f32_e32 v3, 0x3fb8aa3b, v15
	v_fma_f32 v23, v14, s13, -v2
	v_rndne_f32_e32 v24, v2
	v_fma_f32 v25, v15, s13, -v3
	v_rndne_f32_e32 v26, v3
	v_fmac_f32_e32 v23, 0x32a5705f, v14
	v_sub_f32_e32 v2, v2, v24
	v_fmac_f32_e32 v25, 0x32a5705f, v15
	v_sub_f32_e32 v3, v3, v26
	v_add_f32_e32 v2, v2, v23
	v_add_f32_e32 v3, v3, v25
	v_exp_f32_e32 v23, v2
	v_exp_f32_e32 v25, v3
	v_cvt_i32_f32_e32 v24, v24
	v_cvt_i32_f32_e32 v26, v26
	v_cmp_ngt_f32_e32 vcc, s14, v14
	v_ldexp_f32 v23, v23, v24
	v_ldexp_f32 v24, v25, v26
	v_cndmask_b32_e32 v23, 0, v23, vcc
	v_cmp_ngt_f32_e32 vcc, s14, v15
	s_waitcnt vmcnt(0)
	v_mov_b64_e32 v[0:1], v[200:201]
	v_mov_b64_e32 v[2:3], v[202:203]
	v_lshlrev_b32_e32 v32, 16, v1
	v_cndmask_b32_e32 v24, 0, v24, vcc
	v_cmp_nlt_f32_e32 vcc, s28, v14
	v_and_b32_e32 v33, 0xffff0000, v1
	s_nop 0
	v_cndmask_b32_e32 v14, v136, v23, vcc
	v_cmp_nlt_f32_e32 vcc, s28, v15
	v_mul_f32_e64 v20, v20, -v14
	v_mul_f32_e32 v23, 0x3fb8aa3b, v20
	v_cndmask_b32_e32 v15, v136, v24, vcc
	v_mul_f32_e64 v18, v18, -v15
	v_mul_f32_e32 v24, 0x3fb8aa3b, v18
	v_fma_f32 v25, v20, s13, -v23
	v_rndne_f32_e32 v26, v23
	v_fma_f32 v27, v18, s13, -v24
	v_rndne_f32_e32 v28, v24
	v_fmac_f32_e32 v25, 0x32a5705f, v20
	v_sub_f32_e32 v23, v23, v26
	v_fmac_f32_e32 v27, 0x32a5705f, v18
	v_sub_f32_e32 v24, v24, v28
	v_add_f32_e32 v23, v23, v25
	v_cvt_i32_f32_e32 v26, v26
	v_add_f32_e32 v24, v24, v27
	v_exp_f32_e32 v23, v23
	v_cvt_i32_f32_e32 v28, v28
	v_exp_f32_e32 v24, v24
	v_cmp_ngt_f32_e32 vcc, s14, v20
	v_ldexp_f32 v23, v23, v26
	v_lshlrev_b32_e32 v25, 16, v10
	v_ldexp_f32 v24, v24, v28
	v_cndmask_b32_e32 v23, 0, v23, vcc
	v_cmp_ngt_f32_e32 vcc, s14, v18
	v_and_b32_e32 v10, 0xffff0000, v10
	v_mad_u32_u24 v26, v16, s31, v138
	v_cndmask_b32_e32 v24, 0, v24, vcc
	v_cmp_nlt_f32_e32 vcc, s28, v20
	v_mad_u32_u24 v27, v16, s31, v139
	s_nop 0
	v_cndmask_b32_e32 v20, v136, v23, vcc
	v_cmp_nlt_f32_e32 vcc, s28, v18
	v_mul_f32_e32 v20, 0x3e000000, v20
	v_mul_f32_e32 v23, v20, v25
	v_cndmask_b32_e32 v18, v136, v24, vcc
	v_mul_f32_e32 v18, 0x3e000000, v18
	v_mul_f32_e32 v24, v20, v10
	v_mul_f32_e32 v10, v18, v10
	v_mul_f32_e32 v25, v18, v25
	v_cvt_pk_bf16_f32 v23, v23, v133
	v_cvt_pk_bf16_f32 v10, v10, v133
	v_cvt_pk_bf16_f32 v24, v24, v133
	v_cvt_pk_bf16_f32 v25, v25, v133
	ds_write_b16 v22, v23
	ds_write_b16 v22, v24 offset:272
	ds_write_b16 v22, v25 offset:17408
	ds_write_b16 v22, v10 offset:17680
	v_lshlrev_b32_e32 v10, 16, v11
	v_mul_f32_e32 v23, v20, v10
	v_mad_u32_u24 v24, v16, s31, v137
	v_and_b32_e32 v11, 0xffff0000, v11
	v_cvt_pk_bf16_f32 v23, v23, v133
	v_add_u32_e32 v25, v21, v24
	v_mul_f32_e32 v10, v18, v10
	ds_write_b16 v22, v23 offset:544
	v_mul_f32_e32 v23, v20, v11
	v_lshl_add_u32 v25, v25, 1, 0
	v_cvt_pk_bf16_f32 v10, v10, v133
	v_cvt_pk_bf16_f32 v23, v23, v133
	ds_write_b16 v25, v23 offset:272
	ds_write_b16 v22, v10 offset:17952
	v_mul_f32_e32 v10, v18, v11
	v_cvt_pk_bf16_f32 v10, v10, v133
	ds_write_b16 v25, v10 offset:17680
	v_lshlrev_b32_e32 v10, 16, v12
	v_and_b32_e32 v11, 0xffff0000, v12
	v_mul_f32_e32 v12, v20, v10
	v_cvt_pk_bf16_f32 v12, v12, v133
	v_add_u32_e32 v23, v21, v26
	v_mul_f32_e32 v10, v18, v10
	ds_write_b16 v22, v12 offset:1088
	v_mul_f32_e32 v12, v20, v11
	v_lshl_add_u32 v23, v23, 1, 0
	v_cvt_pk_bf16_f32 v10, v10, v133
	v_cvt_pk_bf16_f32 v12, v12, v133
	ds_write_b16 v23, v12 offset:272
	ds_write_b16 v22, v10 offset:18496
	v_mul_f32_e32 v10, v18, v11
	v_cvt_pk_bf16_f32 v10, v10, v133
	ds_write_b16 v23, v10 offset:17680
	v_lshlrev_b32_e32 v10, 16, v13
	v_mul_f32_e32 v12, v20, v10
	v_and_b32_e32 v11, 0xffff0000, v13
	v_cvt_pk_bf16_f32 v12, v12, v133
	ds_write_b16 v22, v12 offset:1632
	v_mul_f32_e32 v12, v20, v11
; __device__ __forceinline__ float bflo(unsigned w) { return __uint_as_float(w << 16); }
; __device__ __forceinline__ float bfhi(unsigned w) { return __uint_as_float(w & 0xffff0000u); }
; __device__ __forceinline__ unsigned short f2bf(float f) { return (unsigned short)(cvt_pk_bf16(f, 0.f) & 0xffffu); }
; __device__ __forceinline__ void retkv_item(PRef p, int layer, int item, unsigned char* shm) {
;     ...
;     for (int i = 0; i < 2; ++i) { const int idx = tid + 512 * i, m = idx >> 3, d8 = (idx & 7) * 8;
;         const u32x4 v = *(const u32x4*)(A + (size_t)(row0 + m) * NIN + C_K + h * 64 + d8);
;         const float pf = 0.125f * expf((float)(127 - m) * lgf), pb = 0.125f * expf((float)m * lgb);
;         const unsigned ww[4] = {v.x, v.y, v.z, v.w};
; #pragma unroll
;         for (int j = 0; j < 4; ++j) { const float lo = bflo(ww[j]), hi = bfhi(ww[j]);
;             kTf[tsw(d8 + 2 * j, m)] = f2bf(lo * pf); kTf[tsw(d8 + 2 * j + 1, m)] = f2bf(hi * pf);
;             kTb[tsw(d8 + 2 * j, m)] = f2bf(lo * pb); kTb[tsw(d8 + 2 * j + 1, m)] = f2bf(hi * pb); } }
; #pragma unroll
;     for (int i = 0; i < 4; ++i) { const int idx = tid + 512 * i, m = idx >> 4, e8 = (idx & 15) * 8;
;         const u32x4 v = *(const u32x4*)(A + (size_t)(row0 + m) * NIN + C_V + h * 128 + e8);
;         const unsigned ww[4] = {v.x, v.y, v.z, v.w};
; #pragma unroll
;         for (int j = 0; j < 4; ++j) { vT[tsw(e8 + 2 * j, m)] = (bf16_t)(ww[j] & 0xffffu); vT[tsw(e8 + 2 * j + 1, m)] = (bf16_t)(ww[j] >> 16); } }
;     __syncthreads();
	v_add_u32_e32 v13, v21, v27
	v_cvt_pk_bf16_f32 v12, v12, v133
	v_lshl_add_u32 v13, v13, 1, 0
	ds_write_b16 v13, v12 offset:272
	v_sub_u32_e32 v12, 0x7f, v19
	v_cvt_f32_i32_e32 v12, v12
	v_mul_f32_e32 v10, v18, v10
	v_cvt_pk_bf16_f32 v10, v10, v133
	ds_write_b16 v22, v10 offset:19040
	v_mul_f32_e32 v10, v18, v11
	v_mul_f32_e64 v11, v12, -v14
	v_mul_f32_e32 v12, 0x3fb8aa3b, v11
	v_fma_f32 v14, v11, s13, -v12
	v_rndne_f32_e32 v18, v12
	v_cvt_pk_bf16_f32 v10, v10, v133
	v_fmac_f32_e32 v14, 0x32a5705f, v11
	v_sub_f32_e32 v12, v12, v18
	ds_write_b16 v13, v10 offset:17680
	v_cvt_f32_i32_e32 v10, v19
	v_add_f32_e32 v12, v12, v14
	v_exp_f32_e32 v12, v12
	v_cvt_i32_f32_e32 v14, v18
	v_mul_f32_e64 v10, v10, -v15
	v_mul_f32_e32 v13, 0x3fb8aa3b, v10
	v_rndne_f32_e32 v15, v13
	v_ldexp_f32 v12, v12, v14
	v_fma_f32 v14, v10, s13, -v13
	v_fmac_f32_e32 v14, 0x32a5705f, v10
	v_sub_f32_e32 v13, v13, v15
	v_add_f32_e32 v13, v13, v14
	v_exp_f32_e32 v13, v13
	v_cvt_i32_f32_e32 v14, v15
	v_cmp_ngt_f32_e32 vcc, s14, v11
	s_nop 1
	v_cndmask_b32_e32 v12, 0, v12, vcc
	v_cmp_nlt_f32_e32 vcc, s28, v11
	s_nop 1
	v_cndmask_b32_e32 v11, v136, v12, vcc
	v_mul_f32_e32 v28, 0x3e000000, v11
	v_ldexp_f32 v11, v13, v14
	v_cmp_ngt_f32_e32 vcc, s14, v10
	s_nop 1
	v_cndmask_b32_e32 v11, 0, v11, vcc
	v_cmp_nlt_f32_e32 vcc, s28, v10
	s_nop 1
	v_cndmask_b32_e32 v10, v136, v11, vcc
	v_mul_f32_e32 v29, 0x3e000000, v10
	v_add_u32_e32 v10, v19, v16
	v_and_b32_e32 v30, 0x7f, v10
	v_lshlrev_b32_e32 v10, 16, v0
	v_mul_f32_e32 v11, v28, v10
	v_mad_u32_u24 v12, v16, s31, v30
	v_and_b32_e32 v0, 0xffff0000, v0
	v_cvt_pk_bf16_f32 v11, v11, v133
	v_lshl_add_u32 v31, v12, 1, 0
	ds_write_b16 v31, v11
	v_mul_f32_e32 v11, v28, v0
	v_mul_f32_e32 v0, v29, v0
	v_cvt_pk_bf16_f32 v0, v0, v133
	ds_write_b16 v31, v0 offset:17680
	v_mul_f32_e32 v0, v28, v32
	v_cvt_pk_bf16_f32 v0, v0, v133
	ds_write_b16 v31, v0 offset:544
	v_mul_f32_e32 v0, v28, v33
	v_cvt_pk_bf16_f32 v14, v0, v133
	v_add_u32_e32 v0, v30, v24
	v_lshl_add_u32 v34, v0, 1, 0
	v_add_u32_e32 v0, s5, v36
	v_mad_i64_i32 v[0:1], s[22:23], v0, s29, v[4:5]
	v_lshl_add_u64 v[0:1], v[0:1], 0, s[10:11]
	v_lshl_add_u64 v[0:1], v[0:1], 0, v[132:133]
	v_mul_f32_e32 v10, v29, v10
	v_add_co_u32_e32 v0, vcc, s30, v0
	v_cvt_pk_bf16_f32 v11, v11, v133
	v_cvt_pk_bf16_f32 v10, v10, v133
	ds_write_b16 v31, v11 offset:272
	s_nop 0
	v_addc_co_u32_e32 v1, vcc, 0, v1, vcc
	ds_write_b16 v31, v10 offset:17408
	global_load_dwordx4 v[10:13], v[0:1], off offset:1024
	v_add_u32_e32 v0, s5, v37
	v_mad_i64_i32 v[0:1], s[22:23], v0, s29, v[4:5]
	v_lshl_add_u64 v[0:1], v[0:1], 0, s[10:11]
	v_lshl_add_u64 v[0:1], v[0:1], 0, v[132:133]
	v_add_co_u32_e32 v0, vcc, s30, v0
	ds_write_b16 v34, v14 offset:272
	s_nop 0
	v_addc_co_u32_e32 v1, vcc, 0, v1, vcc
	global_load_dwordx4 v[14:17], v[0:1], off offset:1024
	v_add_u32_e32 v0, 0x400, v6
	v_ashrrev_i32_e32 v38, 4, v0
	v_add_u32_e32 v0, s5, v38
	v_mad_i64_i32 v[0:1], s[22:23], v0, s29, v[4:5]
	v_lshl_add_u64 v[0:1], v[0:1], 0, s[10:11]
	v_lshl_add_u64 v[0:1], v[0:1], 0, v[132:133]
	v_add_co_u32_e32 v0, vcc, s30, v0
	s_nop 1
	v_addc_co_u32_e32 v1, vcc, 0, v1, vcc
	global_load_dwordx4 v[18:21], v[0:1], off offset:1024
	v_add_u32_e32 v0, 0x600, v6
	v_ashrrev_i32_e32 v39, 4, v0
	v_add_u32_e32 v0, s5, v39
	v_mad_i64_i32 v[0:1], s[22:23], v0, s29, v[4:5]
	v_lshl_add_u64 v[0:1], v[0:1], 0, s[10:11]
	v_lshl_add_u64 v[0:1], v[0:1], 0, v[132:133]
	v_add_co_u32_e32 v0, vcc, s30, v0
	v_add_u32_e32 v4, v30, v26
	s_nop 0
	v_addc_co_u32_e32 v1, vcc, 0, v1, vcc
	global_load_dwordx4 v[22:25], v[0:1], off offset:1024
	v_mul_f32_e32 v0, v29, v32
	v_cvt_pk_bf16_f32 v0, v0, v133
	ds_write_b16 v31, v0 offset:17952
	v_mul_f32_e32 v0, v29, v33
	v_cvt_pk_bf16_f32 v0, v0, v133
	ds_write_b16 v34, v0 offset:17680
	v_lshlrev_b32_e32 v0, 16, v2
	v_and_b32_e32 v1, 0xffff0000, v2
	v_mul_f32_e32 v2, v28, v0
	v_cvt_pk_bf16_f32 v2, v2, v133
	v_mul_f32_e32 v0, v29, v0
	ds_write_b16 v31, v2 offset:1088
	v_mul_f32_e32 v2, v28, v1
	v_lshl_add_u32 v4, v4, 1, 0
	v_cvt_pk_bf16_f32 v0, v0, v133
	v_cvt_pk_bf16_f32 v2, v2, v133
	ds_write_b16 v4, v2 offset:272
	ds_write_b16 v31, v0 offset:18496
	v_mul_f32_e32 v0, v29, v1
	v_cvt_pk_bf16_f32 v0, v0, v133
	ds_write_b16 v4, v0 offset:17680
	v_lshlrev_b32_e32 v0, 16, v3
	v_mul_f32_e32 v2, v28, v0
	v_and_b32_e32 v1, 0xffff0000, v3
	v_cvt_pk_bf16_f32 v2, v2, v133
	v_add_u32_e32 v3, v30, v27
	v_mul_f32_e32 v0, v29, v0
	ds_write_b16 v31, v2 offset:1632
	v_mul_f32_e32 v2, v28, v1
	v_lshl_add_u32 v3, v3, 1, 0
	v_cvt_pk_bf16_f32 v0, v0, v133
	v_cvt_pk_bf16_f32 v2, v2, v133
	ds_write_b16 v3, v2 offset:272
	ds_write_b16 v31, v0 offset:19040
	v_mul_f32_e32 v0, v29, v1
	v_cvt_pk_bf16_f32 v0, v0, v133
	ds_write_b16 v3, v0 offset:17680
	v_add_u32_e32 v0, v36, v9
	v_and_b32_e32 v0, 0x7f, v0
	v_lshlrev_b32_e32 v0, 1, v0
	v_mul_u32_u24_e32 v1, 0x110, v35
	v_add3_u32 v0, 0, v0, v1
	s_waitcnt vmcnt(3)
	ds_write_b16 v0, v10 offset:34816
	ds_write_b16_d16_hi v0, v10 offset:35088
	ds_write_b16 v0, v11 offset:35360
	ds_write_b16_d16_hi v0, v11 offset:35632
	ds_write_b16 v0, v12 offset:35904
	ds_write_b16_d16_hi v0, v12 offset:36176
	ds_write_b16 v0, v13 offset:36448
	ds_write_b16_d16_hi v0, v13 offset:36720
	v_add_u32_e32 v0, v37, v9
	v_and_b32_e32 v0, 0x7f, v0
	v_lshlrev_b32_e32 v0, 1, v0
	v_add3_u32 v0, 0, v0, v1
	s_waitcnt vmcnt(2)
	ds_write_b16 v0, v14 offset:34816
	ds_write_b16_d16_hi v0, v14 offset:35088
	ds_write_b16 v0, v15 offset:35360
	ds_write_b16_d16_hi v0, v15 offset:35632
	ds_write_b16 v0, v16 offset:35904
	ds_write_b16_d16_hi v0, v16 offset:36176
	ds_write_b16 v0, v17 offset:36448
	ds_write_b16_d16_hi v0, v17 offset:36720
	v_add_u32_e32 v0, v38, v9
	v_and_b32_e32 v0, 0x7f, v0
	v_lshlrev_b32_e32 v0, 1, v0
	v_add3_u32 v0, 0, v0, v1
	s_waitcnt vmcnt(1)
	ds_write_b16 v0, v18 offset:34816
	ds_write_b16_d16_hi v0, v18 offset:35088
	ds_write_b16 v0, v19 offset:35360
	ds_write_b16_d16_hi v0, v19 offset:35632
	ds_write_b16 v0, v20 offset:35904
	ds_write_b16_d16_hi v0, v20 offset:36176
	ds_write_b16 v0, v21 offset:36448
	ds_write_b16_d16_hi v0, v21 offset:36720
	v_add_u32_e32 v0, v39, v9
	v_and_b32_e32 v0, 0x7f, v0
	v_lshlrev_b32_e32 v0, 1, v0
	v_add3_u32 v0, 0, v0, v1
	v_lshrrev_b32_e32 v1, 2, v6
	s_waitcnt vmcnt(0)
	ds_write_b16 v0, v22 offset:34816
	ds_write_b16_d16_hi v0, v22 offset:35088
	ds_write_b16 v0, v23 offset:35360
	ds_write_b16_d16_hi v0, v23 offset:35632
	ds_write_b16 v0, v24 offset:35904
	ds_write_b16_d16_hi v0, v24 offset:36176
	ds_write_b16 v0, v25 offset:36448
	ds_write_b16_d16_hi v0, v25 offset:36720
	v_mov_b32_e32 v0, s35
	v_cmp_gt_u32_e32 vcc, s34, v6
	v_and_b32_e32 v9, 48, v1
	v_or_b32_e32 v1, v9, v8
	v_cndmask_b32_e64 v0, v0, 0, vcc
	v_bitop3_b32 v5, v9, 56, v8 bitop3:0xc8
	v_mad_u32_u24 v50, v1, s33, v0
	v_lshlrev_b32_e32 v0, 4, v7
	v_lshlrev_b32_e32 v1, 1, v5
	v_lshlrev_b32_e32 v4, 3, v7
	v_add3_u32 v18, v50, v0, v1
	s_waitcnt lgkmcnt(0)
	s_barrier
; __device__ __forceinline__ void retkv_item(PRef p, int layer, int item, unsigned char* shm) {
;     ...
;     const int dir = wave >> 2, mt = wave & 3;
;     const bf16_t* kT = dir ? kTb : kTf;
;     f32x4 acc[8];
; #pragma unroll
;     for (int nt = 0; nt < 8; ++nt) acc[nt] = (f32x4){0.f, 0.f, 0.f, 0.f};
; #pragma unroll
;     for (int kk = 0; kk < 4; ++kk) { const bf16x8 af = *(const bf16x8*)(kT + tsw(16 * mt + fr, kk * 32 + fq * 8));
; #pragma unroll
;         for (int nt = 0; nt < 8; ++nt) { const bf16x8 bf = *(const bf16x8*)(vT + tsw(16 * nt + fr, kk * 32 + fq * 8));
;             acc[nt] = __builtin_amdgcn_mfma_f32_16x16x32_bf16(af, bf, acc[nt], 0, 0, 0); } }
	ds_read_b128 v[0:3], v18
	v_add_u32_e32 v10, v4, v8
	v_add_u32_e32 v14, v4, v52
	v_add_u32_e32 v22, v4, v54
	v_add_u32_e32 v26, v4, v56
	v_add_u32_e32 v30, v4, v58
	v_add_u32_e32 v61, v4, v60
	v_add_u32_e32 v38, v4, v63
	v_add_u32_e32 v42, v4, v65
	v_and_b32_e32 v10, 56, v10
	v_and_b32_e32 v14, 56, v14
	v_and_b32_e32 v22, 0x78, v22
	v_and_b32_e32 v26, 0x78, v26
	v_and_b32_e32 v30, 0x78, v30
	v_and_b32_e32 v34, 0x78, v61
	v_and_b32_e32 v38, 0x78, v38
	v_and_b32_e32 v42, 0x78, v42
	v_lshl_add_u32 v51, v10, 1, 0
	v_lshlrev_b32_e32 v14, 1, v14
	v_lshlrev_b32_e32 v22, 1, v22
	v_lshlrev_b32_e32 v26, 1, v26
	v_lshlrev_b32_e32 v30, 1, v30
	v_lshlrev_b32_e32 v34, 1, v34
	v_lshlrev_b32_e32 v38, 1, v38
	v_lshlrev_b32_e32 v42, 1, v42
	v_mad_u32_u24 v10, v8, s33, v51
	v_add3_u32 v14, 0, v14, v53
	v_add3_u32 v22, 0, v22, v55
	v_add3_u32 v26, 0, v26, v57
	v_add3_u32 v30, 0, v30, v59
	v_add3_u32 v34, 0, v34, v62
	v_add3_u32 v38, 0, v38, v64
	v_add3_u32 v42, 0, v42, v66
	ds_read_b128 v[10:13], v10 offset:34816
	ds_read_b128 v[14:17], v14 offset:34816
	ds_read_b128 v[18:21], v18 offset:64
	ds_read_b128 v[22:25], v22 offset:34816
	ds_read_b128 v[26:29], v26 offset:34816
	ds_read_b128 v[30:33], v30 offset:34816
	ds_read_b128 v[34:37], v34 offset:34816
	ds_read_b128 v[38:41], v38 offset:34816
	ds_read_b128 v[42:45], v42 offset:34816
	v_or_b32_e32 v68, 32, v4
	s_waitcnt lgkmcnt(8)
	v_mfma_f32_16x16x32_bf16 v[10:13], v[0:3], v[10:13], 0
	v_add_u32_e32 v46, v68, v52
	v_and_b32_e32 v46, 0x78, v46
	v_lshlrev_b32_e32 v46, 1, v46
	s_waitcnt lgkmcnt(7)
	v_mfma_f32_16x16x32_bf16 v[14:17], v[0:3], v[14:17], 0
	v_add3_u32 v46, 0, v46, v53
	ds_read_b128 v[46:49], v46 offset:34816
	v_mov_b32_e32 v132, s3
	s_waitcnt lgkmcnt(6)
	v_mfma_f32_16x16x32_bf16 v[22:25], v[0:3], v[22:25], 0
	s_waitcnt lgkmcnt(5)
	v_mfma_f32_16x16x32_bf16 v[26:29], v[0:3], v[26:29], 0
	s_waitcnt lgkmcnt(4)
	v_mfma_f32_16x16x32_bf16 v[30:33], v[0:3], v[30:33], 0
	s_waitcnt lgkmcnt(3)
	v_mfma_f32_16x16x32_bf16 v[34:37], v[0:3], v[34:37], 0
	s_waitcnt lgkmcnt(2)
	v_mfma_f32_16x16x32_bf16 v[38:41], v[0:3], v[38:41], 0
	s_waitcnt lgkmcnt(1)
	v_mfma_f32_16x16x32_bf16 v[0:3], v[0:3], v[42:45], 0
	v_add_u32_e32 v42, v68, v8
	v_and_b32_e32 v42, 0x78, v42
	v_lshlrev_b32_e32 v42, 1, v42
	v_add3_u32 v42, 0, v42, v67
	ds_read_b128 v[42:45], v42 offset:34816
	s_waitcnt lgkmcnt(1)
	v_mfma_f32_16x16x32_bf16 v[14:17], v[18:21], v[46:49], v[14:17]
	v_add_u32_e32 v46, v68, v56
	v_and_b32_e32 v46, 0x78, v46
	v_lshlrev_b32_e32 v46, 1, v46
	s_waitcnt lgkmcnt(0)
	v_mfma_f32_16x16x32_bf16 v[10:13], v[18:21], v[42:45], v[10:13]
	v_add_u32_e32 v42, v68, v54
	v_and_b32_e32 v42, 0x78, v42
	v_lshlrev_b32_e32 v42, 1, v42
	v_add3_u32 v42, 0, v42, v55
	v_add3_u32 v46, 0, v46, v57
	ds_read_b128 v[42:45], v42 offset:34816
	ds_read_b128 v[46:49], v46 offset:34816
	s_waitcnt lgkmcnt(1)
	v_mfma_f32_16x16x32_bf16 v[22:25], v[18:21], v[42:45], v[22:25]
	v_add_u32_e32 v42, v68, v58
	v_and_b32_e32 v42, 0x78, v42
	v_lshlrev_b32_e32 v42, 1, v42
	s_waitcnt lgkmcnt(0)
	v_mfma_f32_16x16x32_bf16 v[26:29], v[18:21], v[46:49], v[26:29]
	v_add_u32_e32 v46, v68, v60
	v_and_b32_e32 v46, 0x78, v46
	v_lshlrev_b32_e32 v46, 1, v46
	v_add3_u32 v42, 0, v42, v59
	v_add3_u32 v46, 0, v46, v62
	ds_read_b128 v[42:45], v42 offset:34816
	ds_read_b128 v[46:49], v46 offset:34816
	s_waitcnt lgkmcnt(1)
	v_mfma_f32_16x16x32_bf16 v[30:33], v[18:21], v[42:45], v[30:33]
	v_add_u32_e32 v42, v68, v63
	v_and_b32_e32 v42, 56, v42
	v_lshlrev_b32_e32 v42, 1, v42
	s_waitcnt lgkmcnt(0)
	v_mfma_f32_16x16x32_bf16 v[34:37], v[18:21], v[46:49], v[34:37]
	v_add_u32_e32 v46, v68, v65
	v_and_b32_e32 v46, 56, v46
	v_lshlrev_b32_e32 v46, 1, v46
	v_add3_u32 v42, 0, v42, v64
	v_add3_u32 v46, 0, v46, v66
	ds_read_b128 v[42:45], v42 offset:34816
	ds_read_b128 v[46:49], v46 offset:34816
	v_or_b32_e32 v68, 64, v4
	s_waitcnt lgkmcnt(1)
	v_mfma_f32_16x16x32_bf16 v[38:41], v[18:21], v[42:45], v[38:41]
	v_add_u32_e32 v42, v68, v8
	v_and_b32_e32 v42, 0x78, v42
	v_lshlrev_b32_e32 v42, 1, v42
	s_waitcnt lgkmcnt(0)
	v_mfma_f32_16x16x32_bf16 v[0:3], v[18:21], v[46:49], v[0:3]
	v_add_u32_e32 v18, v68, v5
	v_and_b32_e32 v18, 0x78, v18
	v_lshl_add_u32 v18, v18, 1, v50
	ds_read_b128 v[18:21], v18
	v_add_u32_e32 v46, v68, v52
	v_and_b32_e32 v46, 0x78, v46
	v_lshlrev_b32_e32 v46, 1, v46
	v_add3_u32 v42, 0, v42, v67
	v_add3_u32 v46, 0, v46, v53
	ds_read_b128 v[42:45], v42 offset:34816
	ds_read_b128 v[46:49], v46 offset:34816
	s_waitcnt lgkmcnt(1)
	v_mfma_f32_16x16x32_bf16 v[10:13], v[18:21], v[42:45], v[10:13]
	v_add_u32_e32 v42, v68, v54
	v_and_b32_e32 v42, 0x78, v42
	v_lshlrev_b32_e32 v42, 1, v42
	s_waitcnt lgkmcnt(0)
	v_mfma_f32_16x16x32_bf16 v[14:17], v[18:21], v[46:49], v[14:17]
	v_add_u32_e32 v46, v68, v56
	v_and_b32_e32 v46, 0x78, v46
	v_lshlrev_b32_e32 v46, 1, v46
	v_add3_u32 v42, 0, v42, v55
	v_add3_u32 v46, 0, v46, v57
	ds_read_b128 v[42:45], v42 offset:34816
	ds_read_b128 v[46:49], v46 offset:34816
	s_waitcnt lgkmcnt(0)
	v_mfma_f32_16x16x32_bf16 v[26:29], v[18:21], v[46:49], v[26:29]
	v_and_b32_e32 v46, 56, v61
	v_lshlrev_b32_e32 v46, 1, v46
	v_add3_u32 v46, 0, v46, v62
	v_mfma_f32_16x16x32_bf16 v[22:25], v[18:21], v[42:45], v[22:25]
	v_add_u32_e32 v42, v51, v59
	ds_read_b128 v[42:45], v42 offset:34816
	ds_read_b128 v[46:49], v46 offset:34816
	s_waitcnt lgkmcnt(1)
; __device__ __forceinline__ void retkv_item(PRef p, int layer, int item, unsigned char* shm) {
;     ...
; #pragma unroll
;     for (int kk = 0; kk < 4; ++kk) { const bf16x8 af = *(const bf16x8*)(kT + tsw(16 * mt + fr, kk * 32 + fq * 8));
; #pragma unroll
;         for (int nt = 0; nt < 8; ++nt) { const bf16x8 bf = *(const bf16x8*)(vT + tsw(16 * nt + fr, kk * 32 + fq * 8));
;             acc[nt] = __builtin_amdgcn_mfma_f32_16x16x32_bf16(af, bf, acc[nt], 0, 0, 0); } }
;     float* ST = (float*)(p.ws + O_RETST) + ((size_t)((b * 8 + h) * 2 + dir) * 34 + cidx) * 8192;
; #pragma unroll
;     for (int nt = 0; nt < 8; ++nt)
; #pragma unroll
;         for (int r = 0; r < 4; ++r) ST[(16 * mt + fq * 4 + r) * 128 + 16 * nt + fr] = acc[nt][r];
;     __syncthreads();
	v_mfma_f32_16x16x32_bf16 v[30:33], v[18:21], v[42:45], v[30:33]
	v_add_u32_e32 v42, v68, v63
	v_and_b32_e32 v42, 0x78, v42
	v_lshlrev_b32_e32 v42, 1, v42
	s_waitcnt lgkmcnt(0)
	v_mfma_f32_16x16x32_bf16 v[34:37], v[18:21], v[46:49], v[34:37]
	v_add_u32_e32 v46, v68, v65
	v_and_b32_e32 v46, 0x78, v46
	v_lshlrev_b32_e32 v46, 1, v46
	v_add3_u32 v42, 0, v42, v64
	v_add3_u32 v46, 0, v46, v66
	ds_read_b128 v[42:45], v42 offset:34816
	ds_read_b128 v[46:49], v46 offset:34816
	v_or_b32_e32 v4, 0x60, v4
	v_add_u32_e32 v5, v4, v5
	v_and_b32_e32 v5, 0x78, v5
	v_lshl_add_u32 v5, v5, 1, v50
	s_waitcnt lgkmcnt(1)
	v_mfma_f32_16x16x32_bf16 v[38:41], v[18:21], v[42:45], v[38:41]
	s_waitcnt lgkmcnt(0)
	v_mfma_f32_16x16x32_bf16 v[0:3], v[18:21], v[46:49], v[0:3]
	ds_read_b128 v[18:21], v5
	v_add_u32_e32 v5, v4, v8
	v_and_b32_e32 v5, 0x78, v5
	v_lshlrev_b32_e32 v5, 1, v5
	v_add3_u32 v5, 0, v5, v67
	ds_read_b128 v[42:45], v5 offset:34816
	v_add_u32_e32 v5, v4, v52
	v_and_b32_e32 v5, 0x78, v5
	v_lshlrev_b32_e32 v5, 1, v5
	v_add3_u32 v5, 0, v5, v53
	ds_read_b128 v[46:49], v5 offset:34816
	v_add_u32_e32 v5, v4, v54
	v_and_b32_e32 v5, 56, v5
	v_lshlrev_b32_e32 v5, 1, v5
	v_add3_u32 v5, 0, v5, v55
	s_waitcnt lgkmcnt(1)
	v_mfma_f32_16x16x32_bf16 v[10:13], v[18:21], v[42:45], v[10:13]
	ds_read_b128 v[42:45], v5 offset:34816
	v_add_u32_e32 v5, v4, v56
	v_and_b32_e32 v5, 56, v5
	v_lshlrev_b32_e32 v5, 1, v5
	v_add3_u32 v5, 0, v5, v57
	s_waitcnt lgkmcnt(1)
	v_mfma_f32_16x16x32_bf16 v[14:17], v[18:21], v[46:49], v[14:17]
	ds_read_b128 v[46:49], v5 offset:34816
	v_add_u32_e32 v5, v4, v58
	v_and_b32_e32 v5, 0x78, v5
	v_lshlrev_b32_e32 v5, 1, v5
	v_add3_u32 v5, 0, v5, v59
	s_waitcnt lgkmcnt(1)
	v_mfma_f32_16x16x32_bf16 v[22:25], v[18:21], v[42:45], v[22:25]
	ds_read_b128 v[42:45], v5 offset:34816
	v_add_u32_e32 v5, v4, v60
	v_and_b32_e32 v5, 0x78, v5
	v_lshlrev_b32_e32 v5, 1, v5
	v_add3_u32 v5, 0, v5, v62
	s_waitcnt lgkmcnt(1)
	v_mfma_f32_16x16x32_bf16 v[26:29], v[18:21], v[46:49], v[26:29]
	ds_read_b128 v[46:49], v5 offset:34816
	v_add_u32_e32 v5, v4, v63
	v_add_u32_e32 v4, v4, v65
	v_and_b32_e32 v5, 0x78, v5
	v_and_b32_e32 v4, 0x78, v4
	v_lshlrev_b32_e32 v5, 1, v5
	v_lshlrev_b32_e32 v4, 1, v4
	v_add3_u32 v5, 0, v5, v64
	v_add3_u32 v4, 0, v4, v66
	s_waitcnt lgkmcnt(1)
	v_mfma_f32_16x16x32_bf16 v[30:33], v[18:21], v[42:45], v[30:33]
	ds_read_b128 v[42:45], v5 offset:34816
	s_waitcnt lgkmcnt(1)
	v_mfma_f32_16x16x32_bf16 v[34:37], v[18:21], v[46:49], v[34:37]
	ds_read_b128 v[46:49], v4 offset:34816
	v_ashrrev_i32_e32 v4, 8, v6
	v_add_u32_e32 v4, s2, v4
	v_lshlrev_b32_e32 v6, 7, v9
	s_waitcnt lgkmcnt(1)
	v_mfma_f32_16x16x32_bf16 v[38:41], v[18:21], v[42:45], v[38:41]
	v_mad_i64_i32 v[4:5], s[2:3], v4, 34, v[132:133]
	v_lshlrev_b64 v[4:5], 15, v[4:5]
	s_waitcnt lgkmcnt(0)
	v_mfma_f32_16x16x32_bf16 v[0:3], v[18:21], v[46:49], v[0:3]
	v_lshl_or_b32 v18, v7, 9, v6
	v_or_b32_e32 v6, v18, v8
	v_lshl_add_u64 v[4:5], s[18:19], 0, v[4:5]
	v_lshlrev_b32_e32 v132, 2, v6
	v_or_b32_e32 v8, v18, v52
	v_lshl_add_u64 v[6:7], v[4:5], 0, v[132:133]
	v_lshlrev_b32_e32 v132, 2, v8
	v_lshl_add_u64 v[8:9], v[4:5], 0, v[132:133]
	global_store_dword v[6:7], v10, off
	global_store_dword v[6:7], v11, off offset:512
	global_store_dword v[6:7], v12, off offset:1024
	global_store_dword v[6:7], v13, off offset:1536
	global_store_dword v[6:7], v14, off offset:64
	global_store_dword v[8:9], v15, off offset:512
	global_store_dword v[8:9], v16, off offset:1024
	global_store_dword v[8:9], v17, off offset:1536
	global_store_dword v[6:7], v22, off offset:128
	v_or_b32_e32 v8, v18, v54
	v_lshlrev_b32_e32 v132, 2, v8
	v_lshl_add_u64 v[8:9], v[4:5], 0, v[132:133]
	global_store_dword v[8:9], v23, off offset:512
	global_store_dword v[8:9], v24, off offset:1024
	global_store_dword v[8:9], v25, off offset:1536
	global_store_dword v[6:7], v26, off offset:192
	v_or_b32_e32 v8, v18, v56
	v_lshlrev_b32_e32 v132, 2, v8
	v_lshl_add_u64 v[8:9], v[4:5], 0, v[132:133]
	global_store_dword v[8:9], v27, off offset:512
	global_store_dword v[8:9], v28, off offset:1024
	global_store_dword v[8:9], v29, off offset:1536
	global_store_dword v[6:7], v30, off offset:256
	v_or_b32_e32 v8, v18, v58
	v_lshlrev_b32_e32 v132, 2, v8
	v_lshl_add_u64 v[8:9], v[4:5], 0, v[132:133]
	global_store_dword v[8:9], v31, off offset:512
	global_store_dword v[8:9], v32, off offset:1024
	global_store_dword v[8:9], v33, off offset:1536
	global_store_dword v[6:7], v34, off offset:320
	v_or_b32_e32 v8, v18, v60
	v_lshlrev_b32_e32 v132, 2, v8
	v_lshl_add_u64 v[8:9], v[4:5], 0, v[132:133]
	global_store_dword v[8:9], v35, off offset:512
	global_store_dword v[8:9], v36, off offset:1024
	global_store_dword v[8:9], v37, off offset:1536
	global_store_dword v[6:7], v38, off offset:384
	v_or_b32_e32 v8, v18, v63
	v_lshlrev_b32_e32 v132, 2, v8
	v_lshl_add_u64 v[8:9], v[4:5], 0, v[132:133]
	global_store_dword v[8:9], v39, off offset:512
	global_store_dword v[8:9], v40, off offset:1024
	global_store_dword v[8:9], v41, off offset:1536
	global_store_dword v[6:7], v0, off offset:448
	v_or_b32_e32 v0, v18, v65
	v_lshlrev_b32_e32 v132, 2, v0
	v_lshl_add_u64 v[4:5], v[4:5], 0, v[132:133]
	s_mov_b64 s[2:3], 0
	global_store_dword v[4:5], v1, off offset:512
	global_store_dword v[4:5], v2, off offset:1024
	global_store_dword v[4:5], v3, off offset:1536
	s_barrier

; __device__ __forceinline__ float bflo(unsigned w) { return __uint_as_float(w << 16); }
; __device__ __forceinline__ float bfhi(unsigned w) { return __uint_as_float(w & 0xffff0000u); }
; __device__ __forceinline__ unsigned short f2bf(float f) { return (unsigned short)(cvt_pk_bf16(f, 0.f) & 0xffffu); }
; __device__ __forceinline__ void retkv_item(PRef p, int layer, int item, unsigned char* shm) {
;     ...
;     const float lgf = -expf(p.in[17][(layer * 2 + 0) * 8 + h]), lgb = -expf(p.in[17][(layer * 2 + 1) * 8 + h]);
;     const bf16_t* A = (const bf16_t*)(p.ws + O_A);
;     bf16_t* kTf = (bf16_t*)shm; bf16_t* kTb = kTf + 64 * LDK; bf16_t* vT = kTb + 64 * LDK;
; #pragma unroll
;     for (int i = 0; i < 2; ++i) { const int idx = tid + 512 * i, m = idx >> 3, d8 = (idx & 7) * 8;
;         const u32x4 v = *(const u32x4*)(A + (size_t)(row0 + m) * NIN + C_K + h * 64 + d8);
;         const float pf = 0.125f * expf((float)(127 - m) * lgf), pb = 0.125f * expf((float)m * lgb);
;         const unsigned ww[4] = {v.x, v.y, v.z, v.w};
; #pragma unroll
;         for (int j = 0; j < 4; ++j) { const float lo = bflo(ww[j]), hi = bfhi(ww[j]);
;             kTf[tsw(d8 + 2 * j, m)] = f2bf(lo * pf); kTf[tsw(d8 + 2 * j + 1, m)] = f2bf(hi * pf);
;             kTb[tsw(d8 + 2 * j, m)] = f2bf(lo * pb); kTb[tsw(d8 + 2 * j + 1, m)] = f2bf(hi * pb); } }
.LBB0_814:
	s_and_b32 s6, s6, 7
	s_lshl_b32 s12, s6, 2
	v_mov_b32_e32 v0, s12
	global_load_dword v14, v0, s[8:9] offset:64
	global_load_dword v15, v0, s[8:9] offset:96
	v_ashrrev_i32_e32 v2, 3, v6
	v_lshlrev_b32_e32 v9, 3, v6
	v_mov_b64_e32 v[4:5], s[10:11]
	v_add_u32_e32 v0, s7, v2
	v_and_b32_e32 v16, 56, v9
	s_lshl_b32 s22, s6, 7
	v_mad_i64_i32 v[0:1], s[24:25], v0, s30, v[4:5]
	v_lshlrev_b32_e32 v132, 1, v16
	v_lshl_add_u64 v[0:1], v[0:1], 0, s[22:23]
	v_lshl_add_u64 v[0:1], v[0:1], 0, v[132:133]
	v_add_co_u32_e32 v0, vcc, s31, v0
	v_add_u32_e32 v17, 0x200, v6
	s_nop 0
	v_addc_co_u32_e32 v1, vcc, 0, v1, vcc
	global_load_dwordx4 v[10:13], v[0:1], off
	v_sub_u32_e32 v0, 0x7f, v2
	v_ashrrev_i32_e32 v19, 3, v17
	v_cvt_f32_i32_e32 v20, v0
	v_add_u32_e32 v0, v16, v2
	v_add_u32_e32 v1, s7, v19
	v_and_b32_e32 v21, 0x7f, v0
	v_cvt_f32_i32_e32 v18, v2
	v_mad_i64_i32 v[0:1], s[24:25], v1, s30, v[4:5]
	v_mad_u32_u24 v2, v16, s33, v21
	v_lshl_add_u64 v[0:1], v[0:1], 0, s[22:23]
	v_lshl_add_u32 v22, v2, 1, 0
	v_lshl_add_u64 v[0:1], v[0:1], 0, v[132:133]
	v_add_co_u32_e32 v0, vcc, s31, v0
	v_ashrrev_i32_e32 v36, 4, v6
	s_nop 0
	v_addc_co_u32_e32 v1, vcc, 0, v1, vcc
	global_load_dwordx4 v[200:203], v[0:1], off
	v_and_b32_e32 v35, 0x78, v9
	s_lshl_b32 s22, s6, 8
	v_lshlrev_b32_e32 v132, 1, v35
	v_ashrrev_i32_e32 v37, 4, v17
	v_and_b32_e32 v8, 15, v6
	v_bfe_u32 v7, v6, 4, 2
	v_or_b32_e32 v52, 16, v8
	v_or_b32_e32 v54, 32, v8
	v_or_b32_e32 v56, 48, v8
	v_or_b32_e32 v58, 64, v8
	v_or_b32_e32 v60, 0x50, v8
	v_or_b32_e32 v63, 0x60, v8
	v_or_b32_e32 v65, 0x70, v8
	v_mad_u32_u24 v53, v8, s34, v140
	v_mad_u32_u24 v55, v8, s34, v141
	v_mad_u32_u24 v57, v8, s34, v142
	v_mad_u32_u24 v59, v8, s34, v143
	v_mad_u32_u24 v62, v8, s34, v144
	v_mad_u32_u24 v64, v8, s34, v145
	v_mad_u32_u24 v66, v8, s34, v146
	v_mul_u32_u24_e32 v67, 0x110, v8
	s_lshl_b32 s4, s4, 4
	s_lshl_b32 s6, s6, 1
	s_or_b32 s4, s4, s6
	s_waitcnt vmcnt(3)
	v_mul_f32_e32 v2, 0x3fb8aa3b, v14
	s_waitcnt vmcnt(2)
	v_mul_f32_e32 v3, 0x3fb8aa3b, v15
	v_fma_f32 v23, v14, s3, -v2
	v_rndne_f32_e32 v24, v2
	v_fma_f32 v25, v15, s3, -v3
	v_rndne_f32_e32 v26, v3
	v_fmac_f32_e32 v23, 0x32a5705f, v14
	v_sub_f32_e32 v2, v2, v24
	v_fmac_f32_e32 v25, 0x32a5705f, v15
	v_sub_f32_e32 v3, v3, v26
	v_add_f32_e32 v2, v2, v23
	v_add_f32_e32 v3, v3, v25
	v_exp_f32_e32 v23, v2
	v_exp_f32_e32 v25, v3
	v_cvt_i32_f32_e32 v24, v24
	v_cvt_i32_f32_e32 v26, v26
	v_cmp_ngt_f32_e32 vcc, s13, v14
	v_ldexp_f32 v23, v23, v24
	v_ldexp_f32 v24, v25, v26
	v_cndmask_b32_e32 v23, 0, v23, vcc
	v_cmp_ngt_f32_e32 vcc, s13, v15
	s_waitcnt vmcnt(0)
	v_mov_b64_e32 v[0:1], v[200:201]
	v_mov_b64_e32 v[2:3], v[202:203]
	v_lshlrev_b32_e32 v32, 16, v1
	v_cndmask_b32_e32 v24, 0, v24, vcc
	v_cmp_nlt_f32_e32 vcc, s29, v14
	v_and_b32_e32 v33, 0xffff0000, v1
	s_nop 0
	v_cndmask_b32_e32 v14, v136, v23, vcc
	v_cmp_nlt_f32_e32 vcc, s29, v15
	v_mul_f32_e64 v20, v20, -v14
	v_mul_f32_e32 v23, 0x3fb8aa3b, v20
	v_cndmask_b32_e32 v15, v136, v24, vcc
	v_mul_f32_e64 v18, v18, -v15
	v_mul_f32_e32 v24, 0x3fb8aa3b, v18
	v_fma_f32 v25, v20, s3, -v23
	v_rndne_f32_e32 v26, v23
	v_fma_f32 v27, v18, s3, -v24
	v_rndne_f32_e32 v28, v24
	v_fmac_f32_e32 v25, 0x32a5705f, v20
	v_sub_f32_e32 v23, v23, v26
	v_fmac_f32_e32 v27, 0x32a5705f, v18
	v_sub_f32_e32 v24, v24, v28
	v_add_f32_e32 v23, v23, v25
	v_cvt_i32_f32_e32 v26, v26
	v_add_f32_e32 v24, v24, v27
	v_exp_f32_e32 v23, v23
	v_cvt_i32_f32_e32 v28, v28
	v_exp_f32_e32 v24, v24
	v_cmp_ngt_f32_e32 vcc, s13, v20
	v_ldexp_f32 v23, v23, v26
	v_lshlrev_b32_e32 v25, 16, v10
	v_ldexp_f32 v24, v24, v28
	v_cndmask_b32_e32 v23, 0, v23, vcc
	v_cmp_ngt_f32_e32 vcc, s13, v18
	v_and_b32_e32 v10, 0xffff0000, v10
	v_mad_u32_u24 v26, v16, s33, v138
	v_cndmask_b32_e32 v24, 0, v24, vcc
	v_cmp_nlt_f32_e32 vcc, s29, v20
	v_mad_u32_u24 v27, v16, s33, v139
	s_nop 0
	v_cndmask_b32_e32 v20, v136, v23, vcc
	v_cmp_nlt_f32_e32 vcc, s29, v18
	v_mul_f32_e32 v20, 0x3e000000, v20
	v_mul_f32_e32 v23, v20, v25
	v_cndmask_b32_e32 v18, v136, v24, vcc
	v_mul_f32_e32 v18, 0x3e000000, v18
	v_mul_f32_e32 v24, v20, v10
	v_mul_f32_e32 v10, v18, v10
	v_mul_f32_e32 v25, v18, v25
	v_cvt_pk_bf16_f32 v23, v23, v133
	v_cvt_pk_bf16_f32 v10, v10, v133
	v_cvt_pk_bf16_f32 v24, v24, v133
	v_cvt_pk_bf16_f32 v25, v25, v133
	ds_write_b16 v22, v23
	ds_write_b16 v22, v24 offset:272
	ds_write_b16 v22, v25 offset:17408
	ds_write_b16 v22, v10 offset:17680
	v_lshlrev_b32_e32 v10, 16, v11
	v_mul_f32_e32 v23, v20, v10
	v_mad_u32_u24 v24, v16, s33, v137
	v_and_b32_e32 v11, 0xffff0000, v11
	v_cvt_pk_bf16_f32 v23, v23, v133
	v_add_u32_e32 v25, v21, v24
	v_mul_f32_e32 v10, v18, v10
	ds_write_b16 v22, v23 offset:544
	v_mul_f32_e32 v23, v20, v11
	v_lshl_add_u32 v25, v25, 1, 0
	v_cvt_pk_bf16_f32 v10, v10, v133
	v_cvt_pk_bf16_f32 v23, v23, v133
	ds_write_b16 v25, v23 offset:272
	ds_write_b16 v22, v10 offset:17952
	v_mul_f32_e32 v10, v18, v11
	v_cvt_pk_bf16_f32 v10, v10, v133
	ds_write_b16 v25, v10 offset:17680
	v_lshlrev_b32_e32 v10, 16, v12
	v_and_b32_e32 v11, 0xffff0000, v12
	v_mul_f32_e32 v12, v20, v10
	v_cvt_pk_bf16_f32 v12, v12, v133
	v_add_u32_e32 v23, v21, v26
	v_mul_f32_e32 v10, v18, v10
	ds_write_b16 v22, v12 offset:1088
	v_mul_f32_e32 v12, v20, v11
	v_lshl_add_u32 v23, v23, 1, 0
	v_cvt_pk_bf16_f32 v10, v10, v133
	v_cvt_pk_bf16_f32 v12, v12, v133
	ds_write_b16 v23, v12 offset:272
	ds_write_b16 v22, v10 offset:18496
	v_mul_f32_e32 v10, v18, v11
	v_cvt_pk_bf16_f32 v10, v10, v133
	ds_write_b16 v23, v10 offset:17680
	v_lshlrev_b32_e32 v10, 16, v13
	v_mul_f32_e32 v12, v20, v10
	v_and_b32_e32 v11, 0xffff0000, v13
	v_cvt_pk_bf16_f32 v12, v12, v133
	ds_write_b16 v22, v12 offset:1632
	v_mul_f32_e32 v12, v20, v11
; __device__ __forceinline__ float bflo(unsigned w) { return __uint_as_float(w << 16); }
; __device__ __forceinline__ float bfhi(unsigned w) { return __uint_as_float(w & 0xffff0000u); }
; __device__ __forceinline__ unsigned short f2bf(float f) { return (unsigned short)(cvt_pk_bf16(f, 0.f) & 0xffffu); }
; __device__ __forceinline__ void retkv_item(PRef p, int layer, int item, unsigned char* shm) {
;     ...
;     for (int i = 0; i < 2; ++i) { const int idx = tid + 512 * i, m = idx >> 3, d8 = (idx & 7) * 8;
;         const u32x4 v = *(const u32x4*)(A + (size_t)(row0 + m) * NIN + C_K + h * 64 + d8);
;         const float pf = 0.125f * expf((float)(127 - m) * lgf), pb = 0.125f * expf((float)m * lgb);
;         const unsigned ww[4] = {v.x, v.y, v.z, v.w};
; #pragma unroll
;         for (int j = 0; j < 4; ++j) { const float lo = bflo(ww[j]), hi = bfhi(ww[j]);
;             kTf[tsw(d8 + 2 * j, m)] = f2bf(lo * pf); kTf[tsw(d8 + 2 * j + 1, m)] = f2bf(hi * pf);
;             kTb[tsw(d8 + 2 * j, m)] = f2bf(lo * pb); kTb[tsw(d8 + 2 * j + 1, m)] = f2bf(hi * pb); } }
; #pragma unroll
;     for (int i = 0; i < 4; ++i) { const int idx = tid + 512 * i, m = idx >> 4, e8 = (idx & 15) * 8;
;         const u32x4 v = *(const u32x4*)(A + (size_t)(row0 + m) * NIN + C_V + h * 128 + e8);
;         const unsigned ww[4] = {v.x, v.y, v.z, v.w};
; #pragma unroll
;         for (int j = 0; j < 4; ++j) { vT[tsw(e8 + 2 * j, m)] = (bf16_t)(ww[j] & 0xffffu); vT[tsw(e8 + 2 * j + 1, m)] = (bf16_t)(ww[j] >> 16); } }
;     __syncthreads();
	v_add_u32_e32 v13, v21, v27
	v_cvt_pk_bf16_f32 v12, v12, v133
	v_lshl_add_u32 v13, v13, 1, 0
	ds_write_b16 v13, v12 offset:272
	v_sub_u32_e32 v12, 0x7f, v19
	v_cvt_f32_i32_e32 v12, v12
	v_mul_f32_e32 v10, v18, v10
	v_cvt_pk_bf16_f32 v10, v10, v133
	ds_write_b16 v22, v10 offset:19040
	v_mul_f32_e32 v10, v18, v11
	v_mul_f32_e64 v11, v12, -v14
	v_mul_f32_e32 v12, 0x3fb8aa3b, v11
	v_fma_f32 v14, v11, s3, -v12
	v_rndne_f32_e32 v18, v12
	v_cvt_pk_bf16_f32 v10, v10, v133
	v_fmac_f32_e32 v14, 0x32a5705f, v11
	v_sub_f32_e32 v12, v12, v18
	ds_write_b16 v13, v10 offset:17680
	v_cvt_f32_i32_e32 v10, v19
	v_add_f32_e32 v12, v12, v14
	v_exp_f32_e32 v12, v12
	v_cvt_i32_f32_e32 v14, v18
	v_mul_f32_e64 v10, v10, -v15
	v_mul_f32_e32 v13, 0x3fb8aa3b, v10
	v_rndne_f32_e32 v15, v13
	v_ldexp_f32 v12, v12, v14
	v_fma_f32 v14, v10, s3, -v13
	v_fmac_f32_e32 v14, 0x32a5705f, v10
	v_sub_f32_e32 v13, v13, v15
	v_add_f32_e32 v13, v13, v14
	v_exp_f32_e32 v13, v13
	v_cvt_i32_f32_e32 v14, v15
	v_cmp_ngt_f32_e32 vcc, s13, v11
	s_nop 1
	v_cndmask_b32_e32 v12, 0, v12, vcc
	v_cmp_nlt_f32_e32 vcc, s29, v11
	s_nop 1
	v_cndmask_b32_e32 v11, v136, v12, vcc
	v_mul_f32_e32 v28, 0x3e000000, v11
	v_ldexp_f32 v11, v13, v14
	v_cmp_ngt_f32_e32 vcc, s13, v10
	s_nop 1
	v_cndmask_b32_e32 v11, 0, v11, vcc
	v_cmp_nlt_f32_e32 vcc, s29, v10
	s_nop 1
	v_cndmask_b32_e32 v10, v136, v11, vcc
	v_mul_f32_e32 v29, 0x3e000000, v10
	v_add_u32_e32 v10, v19, v16
	v_and_b32_e32 v30, 0x7f, v10
	v_lshlrev_b32_e32 v10, 16, v0
	v_mul_f32_e32 v11, v28, v10
	v_mad_u32_u24 v12, v16, s33, v30
	v_and_b32_e32 v0, 0xffff0000, v0
	v_cvt_pk_bf16_f32 v11, v11, v133
	v_lshl_add_u32 v31, v12, 1, 0
	ds_write_b16 v31, v11
	v_mul_f32_e32 v11, v28, v0
	v_mul_f32_e32 v0, v29, v0
	v_cvt_pk_bf16_f32 v0, v0, v133
	ds_write_b16 v31, v0 offset:17680
	v_mul_f32_e32 v0, v28, v32
	v_cvt_pk_bf16_f32 v0, v0, v133
	ds_write_b16 v31, v0 offset:544
	v_mul_f32_e32 v0, v28, v33
	v_cvt_pk_bf16_f32 v14, v0, v133
	v_add_u32_e32 v0, v30, v24
	v_lshl_add_u32 v34, v0, 1, 0
	v_add_u32_e32 v0, s7, v36
	v_mad_i64_i32 v[0:1], s[24:25], v0, s30, v[4:5]
	v_lshl_add_u64 v[0:1], v[0:1], 0, s[22:23]
	v_lshl_add_u64 v[0:1], v[0:1], 0, v[132:133]
	v_mul_f32_e32 v10, v29, v10
	v_add_co_u32_e32 v0, vcc, s31, v0
	v_cvt_pk_bf16_f32 v11, v11, v133
	v_cvt_pk_bf16_f32 v10, v10, v133
	ds_write_b16 v31, v11 offset:272
	s_nop 0
	v_addc_co_u32_e32 v1, vcc, 0, v1, vcc
	ds_write_b16 v31, v10 offset:17408
	global_load_dwordx4 v[10:13], v[0:1], off offset:1024
	v_add_u32_e32 v0, s7, v37
	v_mad_i64_i32 v[0:1], s[24:25], v0, s30, v[4:5]
	v_lshl_add_u64 v[0:1], v[0:1], 0, s[22:23]
	v_lshl_add_u64 v[0:1], v[0:1], 0, v[132:133]
	v_add_co_u32_e32 v0, vcc, s31, v0
	ds_write_b16 v34, v14 offset:272
	s_nop 0
	v_addc_co_u32_e32 v1, vcc, 0, v1, vcc
	global_load_dwordx4 v[14:17], v[0:1], off offset:1024
	v_add_u32_e32 v0, 0x400, v6
	v_ashrrev_i32_e32 v38, 4, v0
	v_add_u32_e32 v0, s7, v38
	v_mad_i64_i32 v[0:1], s[24:25], v0, s30, v[4:5]
	v_lshl_add_u64 v[0:1], v[0:1], 0, s[22:23]
	v_lshl_add_u64 v[0:1], v[0:1], 0, v[132:133]
	v_add_co_u32_e32 v0, vcc, s31, v0
	s_nop 1
	v_addc_co_u32_e32 v1, vcc, 0, v1, vcc
	global_load_dwordx4 v[18:21], v[0:1], off offset:1024
	v_add_u32_e32 v0, 0x600, v6
	v_ashrrev_i32_e32 v39, 4, v0
	v_add_u32_e32 v0, s7, v39
	v_mad_i64_i32 v[0:1], s[24:25], v0, s30, v[4:5]
	v_lshl_add_u64 v[0:1], v[0:1], 0, s[22:23]
	v_lshl_add_u64 v[0:1], v[0:1], 0, v[132:133]
	v_add_co_u32_e32 v0, vcc, s31, v0
	v_add_u32_e32 v4, v30, v26
	s_nop 0
	v_addc_co_u32_e32 v1, vcc, 0, v1, vcc
	global_load_dwordx4 v[22:25], v[0:1], off offset:1024
	v_mul_f32_e32 v0, v29, v32
	v_cvt_pk_bf16_f32 v0, v0, v133
	ds_write_b16 v31, v0 offset:17952
	v_mul_f32_e32 v0, v29, v33
	v_cvt_pk_bf16_f32 v0, v0, v133
	ds_write_b16 v34, v0 offset:17680
	v_lshlrev_b32_e32 v0, 16, v2
	v_and_b32_e32 v1, 0xffff0000, v2
	v_mul_f32_e32 v2, v28, v0
	v_cvt_pk_bf16_f32 v2, v2, v133
	v_mul_f32_e32 v0, v29, v0
	ds_write_b16 v31, v2 offset:1088
	v_mul_f32_e32 v2, v28, v1
	v_lshl_add_u32 v4, v4, 1, 0
	v_cvt_pk_bf16_f32 v0, v0, v133
	v_cvt_pk_bf16_f32 v2, v2, v133
	ds_write_b16 v4, v2 offset:272
	ds_write_b16 v31, v0 offset:18496
	v_mul_f32_e32 v0, v29, v1
	v_cvt_pk_bf16_f32 v0, v0, v133
	ds_write_b16 v4, v0 offset:17680
	v_lshlrev_b32_e32 v0, 16, v3
	v_mul_f32_e32 v2, v28, v0
	v_and_b32_e32 v1, 0xffff0000, v3
	v_cvt_pk_bf16_f32 v2, v2, v133
	v_add_u32_e32 v3, v30, v27
	v_mul_f32_e32 v0, v29, v0
	ds_write_b16 v31, v2 offset:1632
	v_mul_f32_e32 v2, v28, v1
	v_lshl_add_u32 v3, v3, 1, 0
	v_cvt_pk_bf16_f32 v0, v0, v133
	v_cvt_pk_bf16_f32 v2, v2, v133
	ds_write_b16 v3, v2 offset:272
	ds_write_b16 v31, v0 offset:19040
	v_mul_f32_e32 v0, v29, v1
	v_cvt_pk_bf16_f32 v0, v0, v133
	ds_write_b16 v3, v0 offset:17680
	v_add_u32_e32 v0, v36, v9
	v_and_b32_e32 v0, 0x7f, v0
	v_lshlrev_b32_e32 v0, 1, v0
	v_mul_u32_u24_e32 v1, 0x110, v35
	v_add3_u32 v0, 0, v0, v1
	s_waitcnt vmcnt(3)
	ds_write_b16 v0, v10 offset:34816
	ds_write_b16_d16_hi v0, v10 offset:35088
	ds_write_b16 v0, v11 offset:35360
	ds_write_b16_d16_hi v0, v11 offset:35632
	ds_write_b16 v0, v12 offset:35904
	ds_write_b16_d16_hi v0, v12 offset:36176
	ds_write_b16 v0, v13 offset:36448
	ds_write_b16_d16_hi v0, v13 offset:36720
	v_add_u32_e32 v0, v37, v9
	v_and_b32_e32 v0, 0x7f, v0
	v_lshlrev_b32_e32 v0, 1, v0
	v_add3_u32 v0, 0, v0, v1
	s_waitcnt vmcnt(2)
	ds_write_b16 v0, v14 offset:34816
	ds_write_b16_d16_hi v0, v14 offset:35088
	ds_write_b16 v0, v15 offset:35360
	ds_write_b16_d16_hi v0, v15 offset:35632
	ds_write_b16 v0, v16 offset:35904
	ds_write_b16_d16_hi v0, v16 offset:36176
	ds_write_b16 v0, v17 offset:36448
	ds_write_b16_d16_hi v0, v17 offset:36720
	v_add_u32_e32 v0, v38, v9
	v_and_b32_e32 v0, 0x7f, v0
	v_lshlrev_b32_e32 v0, 1, v0
	v_add3_u32 v0, 0, v0, v1
	s_waitcnt vmcnt(1)
	ds_write_b16 v0, v18 offset:34816
	ds_write_b16_d16_hi v0, v18 offset:35088
	ds_write_b16 v0, v19 offset:35360
	ds_write_b16_d16_hi v0, v19 offset:35632
	ds_write_b16 v0, v20 offset:35904
	ds_write_b16_d16_hi v0, v20 offset:36176
	ds_write_b16 v0, v21 offset:36448
	ds_write_b16_d16_hi v0, v21 offset:36720
	v_add_u32_e32 v0, v39, v9
	v_and_b32_e32 v0, 0x7f, v0
	v_lshlrev_b32_e32 v0, 1, v0
	v_add3_u32 v0, 0, v0, v1
	v_lshrrev_b32_e32 v1, 2, v6
	s_waitcnt vmcnt(0)
	ds_write_b16 v0, v22 offset:34816
	ds_write_b16_d16_hi v0, v22 offset:35088
	ds_write_b16 v0, v23 offset:35360
	ds_write_b16_d16_hi v0, v23 offset:35632
	ds_write_b16 v0, v24 offset:35904
	ds_write_b16_d16_hi v0, v24 offset:36176
	ds_write_b16 v0, v25 offset:36448
	ds_write_b16_d16_hi v0, v25 offset:36720
	v_mov_b32_e32 v0, s35
	v_cmp_gt_u32_e32 vcc, s2, v6
	v_and_b32_e32 v9, 48, v1
	v_or_b32_e32 v1, v9, v8
	v_cndmask_b32_e64 v0, v0, 0, vcc
	v_bitop3_b32 v5, v9, 56, v8 bitop3:0xc8
	v_mad_u32_u24 v50, v1, s34, v0
	v_lshlrev_b32_e32 v0, 4, v7
	v_lshlrev_b32_e32 v1, 1, v5
	v_lshlrev_b32_e32 v4, 3, v7
	v_add3_u32 v18, v50, v0, v1
	s_waitcnt lgkmcnt(0)
	s_barrier
; __device__ __forceinline__ void retkv_item(PRef p, int layer, int item, unsigned char* shm) {
;     ...
;     const int dir = wave >> 2, mt = wave & 3;
;     const bf16_t* kT = dir ? kTb : kTf;
;     f32x4 acc[8];
; #pragma unroll
;     for (int nt = 0; nt < 8; ++nt) acc[nt] = (f32x4){0.f, 0.f, 0.f, 0.f};
; #pragma unroll
;     for (int kk = 0; kk < 4; ++kk) { const bf16x8 af = *(const bf16x8*)(kT + tsw(16 * mt + fr, kk * 32 + fq * 8));
; #pragma unroll
;         for (int nt = 0; nt < 8; ++nt) { const bf16x8 bf = *(const bf16x8*)(vT + tsw(16 * nt + fr, kk * 32 + fq * 8));
;             acc[nt] = __builtin_amdgcn_mfma_f32_16x16x32_bf16(af, bf, acc[nt], 0, 0, 0); } }
	ds_read_b128 v[0:3], v18
	v_add_u32_e32 v10, v4, v8
	v_add_u32_e32 v14, v4, v52
	v_add_u32_e32 v22, v4, v54
	v_add_u32_e32 v26, v4, v56
	v_add_u32_e32 v30, v4, v58
	v_add_u32_e32 v61, v4, v60
	v_add_u32_e32 v38, v4, v63
	v_add_u32_e32 v42, v4, v65
	v_and_b32_e32 v10, 56, v10
	v_and_b32_e32 v14, 56, v14
	v_and_b32_e32 v22, 0x78, v22
	v_and_b32_e32 v26, 0x78, v26
	v_and_b32_e32 v30, 0x78, v30
	v_and_b32_e32 v34, 0x78, v61
	v_and_b32_e32 v38, 0x78, v38
	v_and_b32_e32 v42, 0x78, v42
	v_lshl_add_u32 v51, v10, 1, 0
	v_lshlrev_b32_e32 v14, 1, v14
	v_lshlrev_b32_e32 v22, 1, v22
	v_lshlrev_b32_e32 v26, 1, v26
	v_lshlrev_b32_e32 v30, 1, v30
	v_lshlrev_b32_e32 v34, 1, v34
	v_lshlrev_b32_e32 v38, 1, v38
	v_lshlrev_b32_e32 v42, 1, v42
	v_mad_u32_u24 v10, v8, s34, v51
	v_add3_u32 v14, 0, v14, v53
	v_add3_u32 v22, 0, v22, v55
	v_add3_u32 v26, 0, v26, v57
	v_add3_u32 v30, 0, v30, v59
	v_add3_u32 v34, 0, v34, v62
	v_add3_u32 v38, 0, v38, v64
	v_add3_u32 v42, 0, v42, v66
	ds_read_b128 v[10:13], v10 offset:34816
	ds_read_b128 v[14:17], v14 offset:34816
	ds_read_b128 v[18:21], v18 offset:64
	ds_read_b128 v[22:25], v22 offset:34816
	ds_read_b128 v[26:29], v26 offset:34816
	ds_read_b128 v[30:33], v30 offset:34816
	ds_read_b128 v[34:37], v34 offset:34816
	ds_read_b128 v[38:41], v38 offset:34816
	ds_read_b128 v[42:45], v42 offset:34816
	v_or_b32_e32 v68, 32, v4
	s_waitcnt lgkmcnt(8)
	v_mfma_f32_16x16x32_bf16 v[10:13], v[0:3], v[10:13], 0
	v_add_u32_e32 v46, v68, v52
	v_and_b32_e32 v46, 0x78, v46
	v_lshlrev_b32_e32 v46, 1, v46
	s_waitcnt lgkmcnt(7)
	v_mfma_f32_16x16x32_bf16 v[14:17], v[0:3], v[14:17], 0
	v_add3_u32 v46, 0, v46, v53
	ds_read_b128 v[46:49], v46 offset:34816
	v_mov_b32_e32 v132, s5
	s_waitcnt lgkmcnt(6)
	v_mfma_f32_16x16x32_bf16 v[22:25], v[0:3], v[22:25], 0
	s_waitcnt lgkmcnt(5)
	v_mfma_f32_16x16x32_bf16 v[26:29], v[0:3], v[26:29], 0
	s_waitcnt lgkmcnt(4)
	v_mfma_f32_16x16x32_bf16 v[30:33], v[0:3], v[30:33], 0
	s_waitcnt lgkmcnt(3)
	v_mfma_f32_16x16x32_bf16 v[34:37], v[0:3], v[34:37], 0
	s_waitcnt lgkmcnt(2)
	v_mfma_f32_16x16x32_bf16 v[38:41], v[0:3], v[38:41], 0
	s_waitcnt lgkmcnt(1)
	v_mfma_f32_16x16x32_bf16 v[0:3], v[0:3], v[42:45], 0
	v_add_u32_e32 v42, v68, v8
	v_and_b32_e32 v42, 0x78, v42
	v_lshlrev_b32_e32 v42, 1, v42
	v_add3_u32 v42, 0, v42, v67
	ds_read_b128 v[42:45], v42 offset:34816
	s_waitcnt lgkmcnt(1)
	v_mfma_f32_16x16x32_bf16 v[14:17], v[18:21], v[46:49], v[14:17]
	v_add_u32_e32 v46, v68, v56
	v_and_b32_e32 v46, 0x78, v46
	v_lshlrev_b32_e32 v46, 1, v46
	s_waitcnt lgkmcnt(0)
	v_mfma_f32_16x16x32_bf16 v[10:13], v[18:21], v[42:45], v[10:13]
	v_add_u32_e32 v42, v68, v54
	v_and_b32_e32 v42, 0x78, v42
	v_lshlrev_b32_e32 v42, 1, v42
	v_add3_u32 v42, 0, v42, v55
	v_add3_u32 v46, 0, v46, v57
	ds_read_b128 v[42:45], v42 offset:34816
	ds_read_b128 v[46:49], v46 offset:34816
	s_waitcnt lgkmcnt(1)
	v_mfma_f32_16x16x32_bf16 v[22:25], v[18:21], v[42:45], v[22:25]
	v_add_u32_e32 v42, v68, v58
	v_and_b32_e32 v42, 0x78, v42
	v_lshlrev_b32_e32 v42, 1, v42
	s_waitcnt lgkmcnt(0)
	v_mfma_f32_16x16x32_bf16 v[26:29], v[18:21], v[46:49], v[26:29]
	v_add_u32_e32 v46, v68, v60
	v_and_b32_e32 v46, 0x78, v46
	v_lshlrev_b32_e32 v46, 1, v46
	v_add3_u32 v42, 0, v42, v59
	v_add3_u32 v46, 0, v46, v62
	ds_read_b128 v[42:45], v42 offset:34816
	ds_read_b128 v[46:49], v46 offset:34816
	s_waitcnt lgkmcnt(1)
	v_mfma_f32_16x16x32_bf16 v[30:33], v[18:21], v[42:45], v[30:33]
	v_add_u32_e32 v42, v68, v63
	v_and_b32_e32 v42, 56, v42
	v_lshlrev_b32_e32 v42, 1, v42
	s_waitcnt lgkmcnt(0)
	v_mfma_f32_16x16x32_bf16 v[34:37], v[18:21], v[46:49], v[34:37]
	v_add_u32_e32 v46, v68, v65
	v_and_b32_e32 v46, 56, v46
	v_lshlrev_b32_e32 v46, 1, v46
	v_add3_u32 v42, 0, v42, v64
	v_add3_u32 v46, 0, v46, v66
	ds_read_b128 v[42:45], v42 offset:34816
	ds_read_b128 v[46:49], v46 offset:34816
	v_or_b32_e32 v68, 64, v4
	s_waitcnt lgkmcnt(1)
	v_mfma_f32_16x16x32_bf16 v[38:41], v[18:21], v[42:45], v[38:41]
	v_add_u32_e32 v42, v68, v8
	v_and_b32_e32 v42, 0x78, v42
	v_lshlrev_b32_e32 v42, 1, v42
	s_waitcnt lgkmcnt(0)
	v_mfma_f32_16x16x32_bf16 v[0:3], v[18:21], v[46:49], v[0:3]
	v_add_u32_e32 v18, v68, v5
	v_and_b32_e32 v18, 0x78, v18
	v_lshl_add_u32 v18, v18, 1, v50
	ds_read_b128 v[18:21], v18
	v_add_u32_e32 v46, v68, v52
	v_and_b32_e32 v46, 0x78, v46
	v_lshlrev_b32_e32 v46, 1, v46
	v_add3_u32 v42, 0, v42, v67
	v_add3_u32 v46, 0, v46, v53
	ds_read_b128 v[42:45], v42 offset:34816
	ds_read_b128 v[46:49], v46 offset:34816
	s_waitcnt lgkmcnt(1)
	v_mfma_f32_16x16x32_bf16 v[10:13], v[18:21], v[42:45], v[10:13]
	v_add_u32_e32 v42, v68, v54
	v_and_b32_e32 v42, 0x78, v42
	v_lshlrev_b32_e32 v42, 1, v42
	s_waitcnt lgkmcnt(0)
	v_mfma_f32_16x16x32_bf16 v[14:17], v[18:21], v[46:49], v[14:17]
	v_add_u32_e32 v46, v68, v56
	v_and_b32_e32 v46, 0x78, v46
	v_lshlrev_b32_e32 v46, 1, v46
	v_add3_u32 v42, 0, v42, v55
	v_add3_u32 v46, 0, v46, v57
	ds_read_b128 v[42:45], v42 offset:34816
	ds_read_b128 v[46:49], v46 offset:34816
	s_waitcnt lgkmcnt(0)
	v_mfma_f32_16x16x32_bf16 v[26:29], v[18:21], v[46:49], v[26:29]
	v_and_b32_e32 v46, 56, v61
	v_lshlrev_b32_e32 v46, 1, v46
	v_add3_u32 v46, 0, v46, v62
	v_mfma_f32_16x16x32_bf16 v[22:25], v[18:21], v[42:45], v[22:25]
	v_add_u32_e32 v42, v51, v59
	ds_read_b128 v[42:45], v42 offset:34816
	ds_read_b128 v[46:49], v46 offset:34816
	s_waitcnt lgkmcnt(1)
; __device__ __forceinline__ void retkv_item(PRef p, int layer, int item, unsigned char* shm) {
;     ...
;     for (int kk = 0; kk < 4; ++kk) { const bf16x8 af = *(const bf16x8*)(kT + tsw(16 * mt + fr, kk * 32 + fq * 8));
; #pragma unroll
;         for (int nt = 0; nt < 8; ++nt) { const bf16x8 bf = *(const bf16x8*)(vT + tsw(16 * nt + fr, kk * 32 + fq * 8));
;             acc[nt] = __builtin_amdgcn_mfma_f32_16x16x32_bf16(af, bf, acc[nt], 0, 0, 0); } }
;     float* ST = (float*)(p.ws + O_RETST) + ((size_t)((b * 8 + h) * 2 + dir) * 34 + cidx) * 8192;
; #pragma unroll
;     for (int nt = 0; nt < 8; ++nt)
; #pragma unroll
;         for (int r = 0; r < 4; ++r) ST[(16 * mt + fq * 4 + r) * 128 + 16 * nt + fr] = acc[nt][r];
;     __syncthreads();
	v_mfma_f32_16x16x32_bf16 v[30:33], v[18:21], v[42:45], v[30:33]
	v_add_u32_e32 v42, v68, v63
	v_and_b32_e32 v42, 0x78, v42
	v_lshlrev_b32_e32 v42, 1, v42
	s_waitcnt lgkmcnt(0)
	v_mfma_f32_16x16x32_bf16 v[34:37], v[18:21], v[46:49], v[34:37]
	v_add_u32_e32 v46, v68, v65
	v_and_b32_e32 v46, 0x78, v46
	v_lshlrev_b32_e32 v46, 1, v46
	v_add3_u32 v42, 0, v42, v64
	v_add3_u32 v46, 0, v46, v66
	ds_read_b128 v[42:45], v42 offset:34816
	ds_read_b128 v[46:49], v46 offset:34816
	v_or_b32_e32 v4, 0x60, v4
	v_add_u32_e32 v5, v4, v5
	v_and_b32_e32 v5, 0x78, v5
	v_lshl_add_u32 v5, v5, 1, v50
	s_waitcnt lgkmcnt(1)
	v_mfma_f32_16x16x32_bf16 v[38:41], v[18:21], v[42:45], v[38:41]
	s_waitcnt lgkmcnt(0)
	v_mfma_f32_16x16x32_bf16 v[0:3], v[18:21], v[46:49], v[0:3]
	ds_read_b128 v[18:21], v5
	v_add_u32_e32 v5, v4, v8
	v_and_b32_e32 v5, 0x78, v5
	v_lshlrev_b32_e32 v5, 1, v5
	v_add3_u32 v5, 0, v5, v67
	ds_read_b128 v[42:45], v5 offset:34816
	v_add_u32_e32 v5, v4, v52
	v_and_b32_e32 v5, 0x78, v5
	v_lshlrev_b32_e32 v5, 1, v5
	v_add3_u32 v5, 0, v5, v53
	ds_read_b128 v[46:49], v5 offset:34816
	v_add_u32_e32 v5, v4, v54
	v_and_b32_e32 v5, 56, v5
	v_lshlrev_b32_e32 v5, 1, v5
	v_add3_u32 v5, 0, v5, v55
	s_waitcnt lgkmcnt(1)
	v_mfma_f32_16x16x32_bf16 v[10:13], v[18:21], v[42:45], v[10:13]
	ds_read_b128 v[42:45], v5 offset:34816
	v_add_u32_e32 v5, v4, v56
	v_and_b32_e32 v5, 56, v5
	v_lshlrev_b32_e32 v5, 1, v5
	v_add3_u32 v5, 0, v5, v57
	s_waitcnt lgkmcnt(1)
	v_mfma_f32_16x16x32_bf16 v[14:17], v[18:21], v[46:49], v[14:17]
	ds_read_b128 v[46:49], v5 offset:34816
	v_add_u32_e32 v5, v4, v58
	v_and_b32_e32 v5, 0x78, v5
	v_lshlrev_b32_e32 v5, 1, v5
	v_add3_u32 v5, 0, v5, v59
	s_waitcnt lgkmcnt(1)
	v_mfma_f32_16x16x32_bf16 v[22:25], v[18:21], v[42:45], v[22:25]
	ds_read_b128 v[42:45], v5 offset:34816
	v_add_u32_e32 v5, v4, v60
	v_and_b32_e32 v5, 0x78, v5
	v_lshlrev_b32_e32 v5, 1, v5
	v_add3_u32 v5, 0, v5, v62
	s_waitcnt lgkmcnt(1)
	v_mfma_f32_16x16x32_bf16 v[26:29], v[18:21], v[46:49], v[26:29]
	ds_read_b128 v[46:49], v5 offset:34816
	v_add_u32_e32 v5, v4, v63
	v_add_u32_e32 v4, v4, v65
	v_and_b32_e32 v5, 0x78, v5
	v_and_b32_e32 v4, 0x78, v4
	v_lshlrev_b32_e32 v5, 1, v5
	v_lshlrev_b32_e32 v4, 1, v4
	v_add3_u32 v5, 0, v5, v64
	v_add3_u32 v4, 0, v4, v66
	s_waitcnt lgkmcnt(1)
	v_mfma_f32_16x16x32_bf16 v[30:33], v[18:21], v[42:45], v[30:33]
	ds_read_b128 v[42:45], v5 offset:34816
	s_waitcnt lgkmcnt(1)
	v_mfma_f32_16x16x32_bf16 v[34:37], v[18:21], v[46:49], v[34:37]
	ds_read_b128 v[46:49], v4 offset:34816
	v_ashrrev_i32_e32 v4, 8, v6
	v_add_u32_e32 v4, s4, v4
	v_lshlrev_b32_e32 v6, 7, v9
	s_waitcnt lgkmcnt(1)
	v_mfma_f32_16x16x32_bf16 v[38:41], v[18:21], v[42:45], v[38:41]
	v_mad_i64_i32 v[4:5], s[4:5], v4, 34, v[132:133]
	v_lshlrev_b64 v[4:5], 15, v[4:5]
	s_waitcnt lgkmcnt(0)
	v_mfma_f32_16x16x32_bf16 v[0:3], v[18:21], v[46:49], v[0:3]
	v_lshl_or_b32 v18, v7, 9, v6
	v_or_b32_e32 v6, v18, v8
	v_lshl_add_u64 v[4:5], s[18:19], 0, v[4:5]
	v_lshlrev_b32_e32 v132, 2, v6
	v_or_b32_e32 v8, v18, v52
	v_lshl_add_u64 v[6:7], v[4:5], 0, v[132:133]
	v_lshlrev_b32_e32 v132, 2, v8
	v_lshl_add_u64 v[8:9], v[4:5], 0, v[132:133]
	global_store_dword v[6:7], v10, off
	global_store_dword v[6:7], v11, off offset:512
	global_store_dword v[6:7], v12, off offset:1024
	global_store_dword v[6:7], v13, off offset:1536
	global_store_dword v[6:7], v14, off offset:64
	global_store_dword v[8:9], v15, off offset:512
	global_store_dword v[8:9], v16, off offset:1024
	global_store_dword v[8:9], v17, off offset:1536
	global_store_dword v[6:7], v22, off offset:128
	v_or_b32_e32 v8, v18, v54
	v_lshlrev_b32_e32 v132, 2, v8
	v_lshl_add_u64 v[8:9], v[4:5], 0, v[132:133]
	global_store_dword v[8:9], v23, off offset:512
	global_store_dword v[8:9], v24, off offset:1024
	global_store_dword v[8:9], v25, off offset:1536
	global_store_dword v[6:7], v26, off offset:192
	v_or_b32_e32 v8, v18, v56
	v_lshlrev_b32_e32 v132, 2, v8
	v_lshl_add_u64 v[8:9], v[4:5], 0, v[132:133]
	global_store_dword v[8:9], v27, off offset:512
	global_store_dword v[8:9], v28, off offset:1024
	global_store_dword v[8:9], v29, off offset:1536
	global_store_dword v[6:7], v30, off offset:256
	v_or_b32_e32 v8, v18, v58
	v_lshlrev_b32_e32 v132, 2, v8
	v_lshl_add_u64 v[8:9], v[4:5], 0, v[132:133]
	global_store_dword v[8:9], v31, off offset:512
	global_store_dword v[8:9], v32, off offset:1024
	global_store_dword v[8:9], v33, off offset:1536
	global_store_dword v[6:7], v34, off offset:320
	v_or_b32_e32 v8, v18, v60
	v_lshlrev_b32_e32 v132, 2, v8
	v_lshl_add_u64 v[8:9], v[4:5], 0, v[132:133]
	global_store_dword v[8:9], v35, off offset:512
	global_store_dword v[8:9], v36, off offset:1024
	global_store_dword v[8:9], v37, off offset:1536
	global_store_dword v[6:7], v38, off offset:384
	v_or_b32_e32 v8, v18, v63
	v_lshlrev_b32_e32 v132, 2, v8
	v_lshl_add_u64 v[8:9], v[4:5], 0, v[132:133]
	global_store_dword v[8:9], v39, off offset:512
	global_store_dword v[8:9], v40, off offset:1024
	global_store_dword v[8:9], v41, off offset:1536
	global_store_dword v[6:7], v0, off offset:448
	v_or_b32_e32 v0, v18, v65
	v_lshlrev_b32_e32 v132, 2, v0
	v_lshl_add_u64 v[4:5], v[4:5], 0, v[132:133]
	s_mov_b64 s[4:5], 0
	global_store_dword v[4:5], v1, off offset:512
	global_store_dword v[4:5], v2, off offset:1024
	global_store_dword v[4:5], v3, off offset:1536
	s_barrier
